# gates GEMM epilogue: -log2(e) of the sigmoid's exp2 argument folded into the 16 per-lane column scales once per tile (same f32 math, reassociated), 120 per-element multiplies dropped
# baseline (speedup 1.0000x reference)
.LBB0_3486:
	s_lshl_b32 s7, s58, 8
	s_add_i32 s7, s7, s64
	v_add_u32_e32 v162, s7, v167
	v_ashrrev_i32_e32 v163, 31, v162
	s_lshr_b32 m0, s55, 2
	s_sub_i32 m0, s55, m0
	s_nop 0
	v_lshlrev_b32_e32 v180, 2, v167
	v_add_u32_e32 v180, m0, v180
	v_add_u32_e32 v180, 0x20000, v180
	ds_read_b32 v178, v180
	ds_read_b32 v176, v180 offset:64
	ds_read_b32 v174, v180 offset:128
	ds_read_b32 v172, v180 offset:192
	ds_read_b32 v170, v180 offset:512
	ds_read_b32 v168, v180 offset:576
	ds_read_b32 v166, v180 offset:640
	ds_read_b32 v164, v180 offset:704
	v_cvt_f32_i32_e32 v147, v147
	v_cvt_f32_i32_e32 v146, v146
	v_cvt_f32_i32_e32 v143, v143
	v_cvt_f32_i32_e32 v142, v142
	s_xor_b64 s[44:45], s[10:11], -1
	s_mov_b64 s[48:49], -1
	s_mov_b32 s37, s36
	s_and_b64 vcc, exec, s[44:45]
	s_waitcnt lgkmcnt(0)
	v_mul_f32_e32 v30, 0xbfb8aa3b, v30
	v_mul_f32_e32 v31, 0xbfb8aa3b, v31
	v_mul_f32_e32 v32, 0xbfb8aa3b, v32
	v_mul_f32_e32 v33, 0xbfb8aa3b, v33
	v_mul_f32_e32 v34, 0xbfb8aa3b, v34
	v_mul_f32_e32 v35, 0xbfb8aa3b, v35
	v_mul_f32_e32 v36, 0xbfb8aa3b, v36
	v_mul_f32_e32 v37, 0xbfb8aa3b, v37
	v_mul_f32_e32 v46, 0xbfb8aa3b, v46
	v_mul_f32_e32 v47, 0xbfb8aa3b, v47
	v_mul_f32_e32 v48, 0xbfb8aa3b, v48
	v_mul_f32_e32 v49, 0xbfb8aa3b, v49
	v_mul_f32_e32 v50, 0xbfb8aa3b, v50
	v_mul_f32_e32 v51, 0xbfb8aa3b, v51
	v_mul_f32_e32 v52, 0xbfb8aa3b, v52
	v_mul_f32_e32 v53, 0xbfb8aa3b, v53
	v_pk_mul_f32 v[146:147], v[178:179], v[146:147] op_sel_hi:[0,1]
	v_pk_mul_f32 v[142:143], v[178:179], v[142:143] op_sel_hi:[0,1]
	v_pk_mul_f32 v[180:181], v[50:51], v[146:147]
	v_cvt_f32_i32_e32 v147, v149
	v_cvt_f32_i32_e32 v146, v148
	v_pk_mul_f32 v[182:183], v[46:47], v[142:143]
	v_cvt_f32_i32_e32 v143, v145
	v_cvt_f32_i32_e32 v142, v144
	v_pk_mul_f32 v[146:147], v[178:179], v[146:147] op_sel_hi:[0,1]
	v_pk_mul_f32 v[148:149], v[52:53], v[146:147]
	v_pk_mul_f32 v[142:143], v[178:179], v[142:143] op_sel_hi:[0,1]
	v_pk_mul_f32 v[184:185], v[48:49], v[142:143]
	s_cbranch_vccz .LBB0_3488
	s_mov_b32 s48, s36
	s_mov_b32 s49, s36
	v_pk_mul_f32 v[188:189], s[48:49], v[148:149]
	v_pk_mul_f32 v[144:145], s[36:37], v[180:181]
	v_pk_mul_f32 v[190:191], s[48:49], v[184:185]
	v_pk_mul_f32 v[142:143], s[36:37], v[182:183]
	s_mov_b64 s[48:49], 0
.LBB0_3488:
	s_andn2_b64 vcc, exec, s[48:49]
	s_cbranch_vccnz .LBB0_3490
	v_exp_f32_e32 v2, v180
	v_exp_f32_e32 v5, v182
	v_add_f32_e32 v2, 1.0, v2
	v_rcp_f32_e32 v144, v2
	v_exp_f32_e32 v2, v181
	v_exp_f32_e32 v143, v183
	v_add_f32_e32 v5, 1.0, v5
	v_rcp_f32_e32 v142, v5
	v_add_f32_e32 v2, 1.0, v2
	v_rcp_f32_e32 v145, v2
	v_add_f32_e32 v2, 1.0, v143
	v_exp_f32_e32 v5, v148
	v_exp_f32_e32 v146, v184
	v_rcp_f32_e32 v143, v2
	v_add_f32_e32 v2, 1.0, v5
	v_rcp_f32_e32 v188, v2
	v_add_f32_e32 v2, 1.0, v146
	v_exp_f32_e32 v5, v149
	v_exp_f32_e32 v146, v185
	v_rcp_f32_e32 v190, v2
	v_add_f32_e32 v2, 1.0, v5
	v_rcp_f32_e32 v189, v2
	v_add_f32_e32 v2, 1.0, v146
	v_rcp_f32_e32 v191, v2

.LBB0_3502:
	v_exp_f32_e32 v137, v189
	v_exp_f32_e32 v4, v4
	v_exp_f32_e32 v135, v135
	v_add_f32_e32 v137, 1.0, v137
	v_add_f32_e32 v4, 1.0, v4
	v_rcp_f32_e32 v140, v137
	v_rcp_f32_e32 v137, v4
	v_add_f32_e32 v4, 1.0, v135
	v_mov_b32_e32 v136, v138
	v_exp_f32_e32 v135, v139
	v_exp_f32_e32 v138, v188
	v_exp_f32_e32 v5, v5
	v_exp_f32_e32 v136, v136
	v_exp_f32_e32 v134, v134
	v_rcp_f32_e32 v141, v4
	v_add_f32_e32 v4, 1.0, v135
	v_rcp_f32_e32 v148, v4
	v_add_f32_e32 v4, 1.0, v138
	v_rcp_f32_e32 v178, v4
	v_add_f32_e32 v4, 1.0, v5
	v_add_f32_e32 v136, 1.0, v136
	v_rcp_f32_e32 v149, v4
	v_add_f32_e32 v4, 1.0, v134
	v_rcp_f32_e32 v136, v136
	v_rcp_f32_e32 v179, v4
	s_and_b64 vcc, exec, s[8:9]
	s_mov_b64 s[12:13], -1
	s_cbranch_vccz .LBB0_3500

.LBB0_3513:
	s_andn2_b64 vcc, exec, s[48:49]
	s_cbranch_vccnz .LBB0_3515
	v_exp_f32_e32 v2, v132
	v_exp_f32_e32 v5, v137
	v_add_f32_e32 v2, 1.0, v2
	v_rcp_f32_e32 v126, v2
	v_exp_f32_e32 v2, v133
	v_exp_f32_e32 v4, v136
	v_exp_f32_e32 v130, v139
	v_add_f32_e32 v2, 1.0, v2
	v_rcp_f32_e32 v127, v2
	v_add_f32_e32 v2, 1.0, v5
	v_exp_f32_e32 v128, v134
	v_exp_f32_e32 v129, v138
	v_rcp_f32_e32 v5, v2
	v_add_f32_e32 v2, 1.0, v128
	v_rcp_f32_e32 v128, v2
	v_add_f32_e32 v2, 1.0, v129
	v_exp_f32_e32 v129, v135
	v_rcp_f32_e32 v140, v2
	v_add_f32_e32 v4, 1.0, v4
	v_rcp_f32_e32 v4, v4
	v_add_f32_e32 v2, 1.0, v129
	v_rcp_f32_e32 v129, v2
	v_add_f32_e32 v2, 1.0, v130
	v_rcp_f32_e32 v141, v2

.LBB0_3529:
	v_exp_f32_e32 v5, v141
	v_exp_f32_e32 v121, v124
	v_add_f32_e32 v5, 1.0, v5
	v_exp_f32_e32 v119, v119
	v_rcp_f32_e32 v120, v5
	v_add_f32_e32 v5, 1.0, v121
	v_mov_b32_e32 v4, v122
	v_exp_f32_e32 v122, v123
	v_add_f32_e32 v119, 1.0, v119
	v_exp_f32_e32 v123, v140
	v_rcp_f32_e32 v121, v119
	v_add_f32_e32 v119, 1.0, v122
	v_exp_f32_e32 v4, v4
	v_exp_f32_e32 v122, v125
	v_exp_f32_e32 v118, v118
	v_rcp_f32_e32 v132, v119
	v_add_f32_e32 v119, 1.0, v123
	v_add_f32_e32 v4, 1.0, v4
	v_rcp_f32_e32 v134, v119
	v_add_f32_e32 v119, 1.0, v122
	v_add_f32_e32 v118, 1.0, v118
	v_rcp_f32_e32 v4, v4
	v_rcp_f32_e32 v5, v5
	v_rcp_f32_e32 v133, v119
	v_rcp_f32_e32 v135, v118
	s_and_b64 vcc, exec, s[8:9]
	s_mov_b64 s[48:49], -1
	s_cbranch_vccz .LBB0_3525

.LBB0_3538:
	s_andn2_b64 vcc, exec, s[48:49]
	s_cbranch_vccnz .LBB0_3540
	v_exp_f32_e32 v2, v116
	v_exp_f32_e32 v5, v121
	v_add_f32_e32 v2, 1.0, v2
	v_rcp_f32_e32 v110, v2
	v_exp_f32_e32 v2, v117
	v_exp_f32_e32 v4, v120
	v_exp_f32_e32 v114, v123
	v_add_f32_e32 v2, 1.0, v2
	v_rcp_f32_e32 v111, v2
	v_add_f32_e32 v2, 1.0, v5
	v_exp_f32_e32 v112, v118
	v_exp_f32_e32 v113, v122
	v_rcp_f32_e32 v5, v2
	v_add_f32_e32 v2, 1.0, v112
	v_rcp_f32_e32 v112, v2
	v_add_f32_e32 v2, 1.0, v113
	v_exp_f32_e32 v113, v119
	v_rcp_f32_e32 v124, v2
	v_add_f32_e32 v4, 1.0, v4
	v_rcp_f32_e32 v4, v4
	v_add_f32_e32 v2, 1.0, v113
	v_rcp_f32_e32 v113, v2
	v_add_f32_e32 v2, 1.0, v114
	v_rcp_f32_e32 v125, v2

.LBB0_3554:
	v_exp_f32_e32 v5, v125
	v_exp_f32_e32 v105, v108
	v_add_f32_e32 v5, 1.0, v5
	v_exp_f32_e32 v103, v103
	v_rcp_f32_e32 v104, v5
	v_add_f32_e32 v5, 1.0, v105
	v_mov_b32_e32 v4, v106
	v_exp_f32_e32 v106, v107
	v_add_f32_e32 v103, 1.0, v103
	v_exp_f32_e32 v107, v124
	v_rcp_f32_e32 v105, v103
	v_add_f32_e32 v103, 1.0, v106
	v_exp_f32_e32 v4, v4
	v_exp_f32_e32 v106, v109
	v_exp_f32_e32 v102, v102
	v_rcp_f32_e32 v116, v103
	v_add_f32_e32 v103, 1.0, v107
	v_add_f32_e32 v4, 1.0, v4
	v_rcp_f32_e32 v118, v103
	v_add_f32_e32 v103, 1.0, v106
	v_add_f32_e32 v102, 1.0, v102
	v_rcp_f32_e32 v4, v4
	v_rcp_f32_e32 v5, v5
	v_rcp_f32_e32 v117, v103
	v_rcp_f32_e32 v119, v102
	s_and_b64 vcc, exec, s[8:9]
	s_mov_b64 s[48:49], -1
	s_cbranch_vccz .LBB0_3550

.LBB0_3563:
	s_andn2_b64 vcc, exec, s[48:49]
	s_cbranch_vccnz .LBB0_3565
	v_exp_f32_e32 v2, v100
	v_exp_f32_e32 v5, v105
	v_add_f32_e32 v2, 1.0, v2
	v_rcp_f32_e32 v94, v2
	v_exp_f32_e32 v2, v101
	v_exp_f32_e32 v4, v104
	v_exp_f32_e32 v98, v107
	v_add_f32_e32 v2, 1.0, v2
	v_rcp_f32_e32 v95, v2
	v_add_f32_e32 v2, 1.0, v5
	v_exp_f32_e32 v96, v102
	v_exp_f32_e32 v97, v106
	v_rcp_f32_e32 v5, v2
	v_add_f32_e32 v2, 1.0, v96
	v_rcp_f32_e32 v96, v2
	v_add_f32_e32 v2, 1.0, v97
	v_exp_f32_e32 v97, v103
	v_rcp_f32_e32 v108, v2
	v_add_f32_e32 v4, 1.0, v4
	v_rcp_f32_e32 v4, v4
	v_add_f32_e32 v2, 1.0, v97
	v_rcp_f32_e32 v97, v2
	v_add_f32_e32 v2, 1.0, v98
	v_rcp_f32_e32 v109, v2

.LBB0_3579:
	v_exp_f32_e32 v5, v109
	v_exp_f32_e32 v89, v92
	v_add_f32_e32 v5, 1.0, v5
	v_exp_f32_e32 v87, v87
	v_rcp_f32_e32 v88, v5
	v_add_f32_e32 v5, 1.0, v89
	v_mov_b32_e32 v4, v90
	v_exp_f32_e32 v90, v91
	v_add_f32_e32 v87, 1.0, v87
	v_exp_f32_e32 v91, v108
	v_rcp_f32_e32 v89, v87
	v_add_f32_e32 v87, 1.0, v90
	v_exp_f32_e32 v4, v4
	v_exp_f32_e32 v90, v93
	v_exp_f32_e32 v86, v86
	v_rcp_f32_e32 v100, v87
	v_add_f32_e32 v87, 1.0, v91
	v_add_f32_e32 v4, 1.0, v4
	v_rcp_f32_e32 v102, v87
	v_add_f32_e32 v87, 1.0, v90
	v_add_f32_e32 v86, 1.0, v86
	v_rcp_f32_e32 v4, v4
	v_rcp_f32_e32 v5, v5
	v_rcp_f32_e32 v101, v87
	v_rcp_f32_e32 v103, v86
	s_and_b64 vcc, exec, s[8:9]
	s_mov_b64 s[48:49], -1
	s_cbranch_vccz .LBB0_3575

.LBB0_3588:
	s_andn2_b64 vcc, exec, s[48:49]
	s_cbranch_vccnz .LBB0_3590
	v_exp_f32_e32 v2, v84
	v_exp_f32_e32 v5, v89
	v_add_f32_e32 v2, 1.0, v2
	v_rcp_f32_e32 v78, v2
	v_exp_f32_e32 v2, v85
	v_exp_f32_e32 v4, v88
	v_exp_f32_e32 v82, v91
	v_add_f32_e32 v2, 1.0, v2
	v_rcp_f32_e32 v79, v2
	v_add_f32_e32 v2, 1.0, v5
	v_exp_f32_e32 v80, v86
	v_exp_f32_e32 v81, v90
	v_rcp_f32_e32 v5, v2
	v_add_f32_e32 v2, 1.0, v80
	v_rcp_f32_e32 v80, v2
	v_add_f32_e32 v2, 1.0, v81
	v_exp_f32_e32 v81, v87
	v_rcp_f32_e32 v92, v2
	v_add_f32_e32 v4, 1.0, v4
	v_rcp_f32_e32 v4, v4
	v_add_f32_e32 v2, 1.0, v81
	v_rcp_f32_e32 v81, v2
	v_add_f32_e32 v2, 1.0, v82
	v_rcp_f32_e32 v93, v2

.LBB0_3604:
	v_exp_f32_e32 v5, v93
	v_exp_f32_e32 v73, v76
	v_add_f32_e32 v5, 1.0, v5
	v_exp_f32_e32 v71, v71
	v_rcp_f32_e32 v72, v5
	v_add_f32_e32 v5, 1.0, v73
	v_mov_b32_e32 v4, v74
	v_exp_f32_e32 v74, v75
	v_add_f32_e32 v71, 1.0, v71
	v_exp_f32_e32 v75, v92
	v_rcp_f32_e32 v73, v71
	v_add_f32_e32 v71, 1.0, v74
	v_exp_f32_e32 v4, v4
	v_exp_f32_e32 v74, v77
	v_exp_f32_e32 v70, v70
	v_rcp_f32_e32 v84, v71
	v_add_f32_e32 v71, 1.0, v75
	v_add_f32_e32 v4, 1.0, v4
	v_rcp_f32_e32 v86, v71
	v_add_f32_e32 v71, 1.0, v74
	v_add_f32_e32 v70, 1.0, v70
	v_rcp_f32_e32 v4, v4
	v_rcp_f32_e32 v5, v5
	v_rcp_f32_e32 v85, v71
	v_rcp_f32_e32 v87, v70
	s_and_b64 vcc, exec, s[8:9]
	s_mov_b64 s[48:49], -1
	s_cbranch_vccz .LBB0_3600

.LBB0_3613:
	s_andn2_b64 vcc, exec, s[48:49]
	s_cbranch_vccnz .LBB0_3615
	v_exp_f32_e32 v2, v68
	v_exp_f32_e32 v5, v73
	v_add_f32_e32 v2, 1.0, v2
	v_rcp_f32_e32 v62, v2
	v_exp_f32_e32 v2, v69
	v_exp_f32_e32 v4, v72
	v_exp_f32_e32 v66, v75
	v_add_f32_e32 v2, 1.0, v2
	v_rcp_f32_e32 v63, v2
	v_add_f32_e32 v2, 1.0, v5
	v_exp_f32_e32 v64, v70
	v_exp_f32_e32 v65, v74
	v_rcp_f32_e32 v5, v2
	v_add_f32_e32 v2, 1.0, v64
	v_rcp_f32_e32 v64, v2
	v_add_f32_e32 v2, 1.0, v65
	v_exp_f32_e32 v65, v71
	v_rcp_f32_e32 v76, v2
	v_add_f32_e32 v4, 1.0, v4
	v_rcp_f32_e32 v4, v4
	v_add_f32_e32 v2, 1.0, v65
	v_rcp_f32_e32 v65, v2
	v_add_f32_e32 v2, 1.0, v66
	v_rcp_f32_e32 v77, v2

.LBB0_3629:
	v_exp_f32_e32 v5, v77
	v_exp_f32_e32 v57, v60
	v_add_f32_e32 v5, 1.0, v5
	v_exp_f32_e32 v55, v55
	v_rcp_f32_e32 v56, v5
	v_add_f32_e32 v5, 1.0, v57
	v_mov_b32_e32 v4, v58
	v_exp_f32_e32 v58, v59
	v_add_f32_e32 v55, 1.0, v55
	v_exp_f32_e32 v59, v76
	v_rcp_f32_e32 v57, v55
	v_add_f32_e32 v55, 1.0, v58
	v_exp_f32_e32 v4, v4
	v_exp_f32_e32 v58, v61
	v_exp_f32_e32 v54, v54
	v_rcp_f32_e32 v68, v55
	v_add_f32_e32 v55, 1.0, v59
	v_add_f32_e32 v4, 1.0, v4
	v_rcp_f32_e32 v70, v55
	v_add_f32_e32 v55, 1.0, v58
	v_add_f32_e32 v54, 1.0, v54
	v_rcp_f32_e32 v4, v4
	v_rcp_f32_e32 v5, v5
	v_rcp_f32_e32 v69, v55
	v_rcp_f32_e32 v71, v54
	s_and_b64 vcc, exec, s[8:9]
	s_mov_b64 s[48:49], -1
	s_cbranch_vccz .LBB0_3625

.LBB0_3638:
	s_andn2_b64 vcc, exec, s[48:49]
	s_cbranch_vccnz .LBB0_3640
	v_exp_f32_e32 v2, v44
	v_exp_f32_e32 v5, v57
	v_add_f32_e32 v2, 1.0, v2
	v_rcp_f32_e32 v38, v2
	v_exp_f32_e32 v2, v45
	v_exp_f32_e32 v4, v56
	v_exp_f32_e32 v42, v59
	v_add_f32_e32 v2, 1.0, v2
	v_rcp_f32_e32 v39, v2
	v_add_f32_e32 v2, 1.0, v5
	v_exp_f32_e32 v40, v54
	v_exp_f32_e32 v41, v58
	v_rcp_f32_e32 v5, v2
	v_add_f32_e32 v2, 1.0, v40
	v_rcp_f32_e32 v40, v2
	v_add_f32_e32 v2, 1.0, v41
	v_exp_f32_e32 v41, v55
	v_rcp_f32_e32 v60, v2
	v_add_f32_e32 v4, 1.0, v4
	v_rcp_f32_e32 v4, v4
	v_add_f32_e32 v2, 1.0, v41
	v_rcp_f32_e32 v41, v2
	v_add_f32_e32 v2, 1.0, v42
	v_rcp_f32_e32 v61, v2

.LBB0_3654:
	v_exp_f32_e32 v5, v61
	v_exp_f32_e32 v25, v28
	v_add_f32_e32 v5, 1.0, v5
	v_exp_f32_e32 v23, v23
	v_rcp_f32_e32 v24, v5
	v_add_f32_e32 v5, 1.0, v25
	v_mov_b32_e32 v4, v26
	v_exp_f32_e32 v26, v27
	v_add_f32_e32 v23, 1.0, v23
	v_exp_f32_e32 v27, v60
	v_rcp_f32_e32 v25, v23
	v_add_f32_e32 v23, 1.0, v26
	v_exp_f32_e32 v4, v4
	v_exp_f32_e32 v26, v29
	v_exp_f32_e32 v22, v22
	v_rcp_f32_e32 v44, v23
	v_add_f32_e32 v23, 1.0, v27
	v_add_f32_e32 v4, 1.0, v4
	v_rcp_f32_e32 v54, v23
	v_add_f32_e32 v23, 1.0, v26
	v_add_f32_e32 v22, 1.0, v22
	v_rcp_f32_e32 v4, v4
	v_rcp_f32_e32 v5, v5
	v_rcp_f32_e32 v45, v23
	v_rcp_f32_e32 v55, v22
	s_and_b64 vcc, exec, s[8:9]
	s_mov_b64 s[48:49], -1
	s_cbranch_vccz .LBB0_3650

.LBB0_3663:
	s_andn2_b64 vcc, exec, s[48:49]
	s_cbranch_vccnz .LBB0_3665
	v_exp_f32_e32 v2, v20
	v_exp_f32_e32 v5, v25
	v_add_f32_e32 v2, 1.0, v2
	v_rcp_f32_e32 v14, v2
	v_exp_f32_e32 v2, v21
	v_exp_f32_e32 v4, v24
	v_exp_f32_e32 v18, v27
	v_add_f32_e32 v2, 1.0, v2
	v_rcp_f32_e32 v15, v2
	v_add_f32_e32 v2, 1.0, v5
	v_exp_f32_e32 v16, v22
	v_exp_f32_e32 v17, v26
	v_rcp_f32_e32 v5, v2
	v_add_f32_e32 v2, 1.0, v16
	v_rcp_f32_e32 v16, v2
	v_add_f32_e32 v2, 1.0, v17
	v_exp_f32_e32 v17, v23
	v_rcp_f32_e32 v28, v2
	v_add_f32_e32 v4, 1.0, v4
	v_rcp_f32_e32 v4, v4
	v_add_f32_e32 v2, 1.0, v17
	v_rcp_f32_e32 v17, v2
	v_add_f32_e32 v2, 1.0, v18
	v_rcp_f32_e32 v29, v2

.LBB0_3680:
	v_exp_f32_e32 v5, v29
	v_exp_f32_e32 v9, v12
	v_add_f32_e32 v5, 1.0, v5
	v_exp_f32_e32 v7, v7
	v_rcp_f32_e32 v8, v5
	v_add_f32_e32 v5, 1.0, v9
	v_mov_b32_e32 v4, v10
	v_exp_f32_e32 v10, v11
	v_add_f32_e32 v7, 1.0, v7
	v_exp_f32_e32 v11, v28
	v_rcp_f32_e32 v9, v7
	v_add_f32_e32 v7, 1.0, v10
	v_exp_f32_e32 v4, v4
	v_exp_f32_e32 v10, v13
	v_exp_f32_e32 v6, v6
	v_rcp_f32_e32 v20, v7
	v_add_f32_e32 v7, 1.0, v11
	v_add_f32_e32 v4, 1.0, v4
	v_rcp_f32_e32 v22, v7
	v_add_f32_e32 v7, 1.0, v10
	v_add_f32_e32 v6, 1.0, v6
	v_rcp_f32_e32 v4, v4
	v_rcp_f32_e32 v5, v5
	v_rcp_f32_e32 v21, v7
	v_rcp_f32_e32 v23, v6
	s_and_b64 vcc, exec, s[8:9]
	s_mov_b64 s[8:9], -1
	s_cbranch_vccz .LBB0_3675
